# RESID epilogue: no vmcnt(0) drain before the residual prefetch loads (counted waits cover them)
# speedup vs baseline: 1.0028x; 1.0028x over previous
; #define LAS __attribute__((address_space(3)))
; DI u32x2 pk4(f32x4 v) { u32x2 r; r.x = cvt_pk(v[0], v[1]); r.y = cvt_pk(v[2], v[3]); return r; }
; DI void gemm_phase(LAS unsigned char* lds, const GemmDesc& d, float* __restrict__ X) {
;     ...
;       LAS float* red = (LAS float*)(lds + 133120); const float alpha = d.K == FF ? 0.5f : 1.f;
; #pragma unroll
;       for (int ai = 0; ai < 2; ++ai)
; #pragma unroll
;         for (int m = 0; m < 4; ++m) {
;           const int row = pm * 256 + 128 * ai + 16 * m + rb; float ss = 0.f;
; #pragma unroll
;           for (int bj = 0; bj < 2; ++bj) {
;             const size_t o = (size_t)row * DM + pn * 256 + 128 * bj + cb;
;             const u32x4 xw = *(const u32x4*)(d.O0 + o); u32x4 ow;
; #pragma unroll
;             for (int n = 0; n < 2; ++n) {
;               const unsigned w0 = n ? xw.z : xw.x, w1 = n ? xw.w : xw.y;
;               f32x4 xo; xo[0] = __uint_as_float(w0 << 16); xo[1] = __uint_as_float(w0 & 0xffff0000u); xo[2] = __uint_as_float(w1 << 16); xo[3] = __uint_as_float(w1 & 0xffff0000u);
;               const f32x4 xn = xo + acc[ai][bj][m][n] * alpha;
;               ss += (xn[0] * xn[0] + xn[1] * xn[1]) + (xn[2] * xn[2] + xn[3] * xn[3]);
;               const u32x2 pw = pk4(xn); if (n) { ow.z = pw.x; ow.w = pw.y; } else { ow.x = pw.x; ow.y = pw.y; }
;             }
;             *(u32x4*)(d.O0 + o) = ow;
;           }
;           ss += __shfl_xor(ss, 16); ss += __shfl_xor(ss, 32);
;           if (fq == 0) red[wc * 256 + 128 * ai + 16 * m + rb] = ss;
.LBB0_522:
	s_andn2_b64 vcc, exec, s[44:45]
	s_cbranch_vccnz .LBB0_542
	s_lshl_b32 s46, s97, 8
	s_lshl_b32 s6, s68, 8
	s_nop 0
	v_add_u32_e32 v132, s46, v163
	s_ashr_i32 s14, s6, 31
	s_waitcnt lgkmcnt(0)
	v_or_b32_e32 v130, s6, v182
	v_mov_b32_e32 v131, s14
	v_ashrrev_i32_e32 v133, 31, v132
	v_lshl_add_u64 v[134:135], v[130:131], 1, s[28:29]
	v_lshlrev_b64 v[136:137], 11, v[132:133]
	v_lshl_add_u64 v[138:139], v[134:135], 0, v[136:137]
	v_lshlrev_b32_e32 v243, 11, v132
	v_lshl_add_u32 v243, v130, 1, v243
	global_load_dwordx4 v[142:145], v243, s[28:29]
	global_load_dwordx4 v[166:169], v243, s[28:29] offset:256
	v_add_u32_e32 v252, 0x8000, v243
	global_load_dwordx4 v[170:173], v252, s[28:29]
	v_add_u32_e32 v252, 0x8000, v243
	global_load_dwordx4 v[184:187], v252, s[28:29] offset:256
	v_add_u32_e32 v252, 0x10000, v243
	global_load_dwordx4 v[188:191], v252, s[28:29]
	v_add_u32_e32 v252, 0x10000, v243
	global_load_dwordx4 v[216:219], v252, s[28:29] offset:256
	v_add_u32_e32 v252, 0x18000, v243
	global_load_dwordx4 v[222:225], v252, s[28:29]
	v_add_u32_e32 v252, 0x18000, v243
	global_load_dwordx4 v[226:229], v252, s[28:29] offset:256
	v_add_u32_e32 v252, 0x40000, v243
	global_load_dwordx4 v[230:233], v252, s[28:29]
	v_add_u32_e32 v252, 0x40000, v243
	global_load_dwordx4 v[234:237], v252, s[28:29] offset:256
	v_add_u32_e32 v252, 0x48000, v243
	global_load_dwordx4 v[244:247], v252, s[28:29]
	v_add_u32_e32 v252, 0x48000, v243
	global_load_dwordx4 v[248:251], v252, s[28:29] offset:256
	s_waitcnt vmcnt(11)
	v_mov_b32_e32 v134, v142
	v_mov_b32_e32 v135, v143
	v_mov_b32_e32 v136, v144
	v_mov_b32_e32 v137, v145
	v_add_u32_e32 v252, 0x50000, v243
	global_load_dwordx4 v[142:145], v252, s[28:29]
	s_lshl_b32 s6, s20, 10
	s_add_i32 s6, s6, 0
	s_add_i32 s6, s6, 0x20800
	v_cmp_eq_u32_e32 vcc, 0, v179
	v_lshl_add_u32 v0, v163, 2, s6
	s_nop 0
	v_lshlrev_b32_e32 v140, 16, v134
	v_and_b32_e32 v141, 0xffff0000, v134
	v_lshlrev_b32_e32 v134, 16, v135
	v_and_b32_e32 v135, 0xffff0000, v135
	v_pk_fma_f32 v[128:129], s[66:67], v[128:129], v[134:135]
	v_pk_fma_f32 v[126:127], s[60:61], v[126:127], v[140:141]
	v_mul_f32_e32 v134, v129, v129
	v_mul_f32_e32 v133, v127, v127
	v_fmac_f32_e32 v133, v126, v126
	v_fmac_f32_e32 v134, v128, v128
	v_add_f32_e32 v133, v133, v134
	v_cvt_pk_bf16_f32 v126, v126, v127
	v_cvt_pk_bf16_f32 v127, v128, v129
	v_lshlrev_b32_e32 v128, 16, v136
	v_and_b32_e32 v129, 0xffff0000, v136
	v_lshlrev_b32_e32 v134, 16, v137
	v_and_b32_e32 v135, 0xffff0000, v137
	v_pk_fma_f32 v[124:125], s[66:67], v[124:125], v[134:135]
	v_pk_fma_f32 v[122:123], s[60:61], v[122:123], v[128:129]
	v_mul_f32_e32 v129, v125, v125
	v_mul_f32_e32 v128, v123, v123
	v_fmac_f32_e32 v128, v122, v122
	v_fmac_f32_e32 v129, v124, v124
	v_add_f32_e32 v128, v128, v129
	v_add_f32_e32 v133, v133, v128
	v_cvt_pk_bf16_f32 v128, v122, v123
	v_cvt_pk_bf16_f32 v129, v124, v125
	s_waitcnt vmcnt(11)
	v_mov_b32_e32 v122, v166
	v_mov_b32_e32 v123, v167
	v_mov_b32_e32 v124, v168
	v_mov_b32_e32 v125, v169
	v_add_u32_e32 v252, 0x50000, v243
	global_load_dwordx4 v[166:169], v252, s[28:29] offset:256
	s_nop 0
	global_store_dwordx4 v[138:139], v[126:129], off
	s_nop 0
	s_nop 0
	v_lshlrev_b32_e32 v126, 16, v122
	v_and_b32_e32 v127, 0xffff0000, v122
	v_lshlrev_b32_e32 v122, 16, v123
	v_and_b32_e32 v123, 0xffff0000, v123
	v_pk_fma_f32 v[120:121], s[66:67], v[120:121], v[122:123]
	v_pk_fma_f32 v[118:119], s[60:61], v[118:119], v[126:127]
	v_mul_f32_e32 v123, v121, v121
	v_mul_f32_e32 v122, v119, v119
	v_fmac_f32_e32 v122, v118, v118
	v_fmac_f32_e32 v123, v120, v120
	v_add_f32_e32 v122, v122, v123
	v_add_f32_e32 v126, v133, v122
	v_cvt_pk_bf16_f32 v118, v118, v119
	v_cvt_pk_bf16_f32 v119, v120, v121
	v_lshlrev_b32_e32 v120, 16, v124
	v_and_b32_e32 v121, 0xffff0000, v124
	v_lshlrev_b32_e32 v122, 16, v125
	v_and_b32_e32 v123, 0xffff0000, v125
	v_pk_fma_f32 v[116:117], s[66:67], v[116:117], v[122:123]
	v_pk_fma_f32 v[114:115], s[60:61], v[114:115], v[120:121]
	v_mul_f32_e32 v121, v117, v117
	v_mul_f32_e32 v120, v115, v115
	v_fmac_f32_e32 v120, v114, v114
	v_fmac_f32_e32 v121, v116, v116
	v_add_f32_e32 v120, v120, v121
	v_add_f32_e32 v122, v120, v126
	v_cvt_pk_bf16_f32 v120, v114, v115
	v_and_b32_e32 v115, 64, v221
	v_xor_b32_e32 v114, 16, v221
	v_add_u32_e32 v115, 64, v115
	v_cmp_lt_i32_e64 s[44:45], v114, v115
	v_cvt_pk_bf16_f32 v121, v116, v117
	v_xor_b32_e32 v117, 32, v221
	global_store_dwordx4 v[138:139], v[118:121], off offset:256
	v_cndmask_b32_e64 v114, v221, v114, s[44:45]
	v_lshlrev_b32_e32 v116, 2, v114
	ds_bpermute_b32 v114, v116, v122
	v_cmp_lt_i32_e64 s[44:45], v117, v115
	s_waitcnt lgkmcnt(0)
	v_add_f32_e32 v114, v122, v114
	v_cndmask_b32_e64 v115, v221, v117, s[44:45]
	v_lshlrev_b32_e32 v117, 2, v115
	ds_bpermute_b32 v115, v117, v114
	s_and_saveexec_b64 s[44:45], vcc
	s_cbranch_execz .LBB0_525
	s_waitcnt lgkmcnt(0)
	v_add_f32_e32 v114, v114, v115
	ds_write_b32 v0, v114
